# SWA: for the three fully-inside-window key tiles the 16 per-element exec-masked bias LDS loads (one wait each) become 16 batched ds_read_b32 + one wait when the block is not the first of the sequence
# speedup vs baseline: 1.0092x; 1.0092x over previous
; #define LAS __attribute__((address_space(3)))
; #define MFMA32(a, b, c) __builtin_amdgcn_mfma_f32_32x32x16_bf16((a), (b), (c), 0, 0, 0)
; __device__ __forceinline__ int crow(int i, int hh) { return (i & 3) + 8 * (i >> 2) + 4 * hh; }
; __device__ __forceinline__ void swa_unit(LAS unsigned char* lds, const bf16_t* Z1, const bf16_t* VTA, const float* bias2, const float* sinks, bf16_t* OA, int b, int kvh, int qblk, int wv) {
;     ...
;         for (int kt = 0; kt < 5; ++kt) {
;             const int kb = q0w + 32 * kt;
;             if (Q0 == 0 && kb + 31 < 128) continue;
;             f32x16 sc;
; #pragma unroll
;             for (int i = 0; i < 16; ++i) sc[i] = 0.f;
; #pragma unroll
;             for (int s = 0; s < 4; ++s) { const bf16x8 a = *(const LAS bf16x8*)(lds + (kb + r) * SK_ROW + s * 32 + hh * 16); sc = MFMA32(a, qf[s], sc); }
; #pragma unroll
;             for (int i = 0; i < 16; ++i) { const int c = crow(i, hh), dist = 128 - 32 * kt + r - c;
;                 const bool ok = (dist >= 0) && (dist < 128) && (Q0 > 0 || kb + c >= 128);
;                 sc[i] = ok ? sc[i] + bl[dist & 127] : -INFINITY; }
.LBB0_758:
	s_add_i32 s25, s30, 32
	s_xor_b64 s[28:29], s[28:29], -1
	s_or_b32 s16, s25, 31
	s_cmpk_lt_i32 s16, 0x80
	s_cselect_b64 s[16:17], -1, 0
	s_and_b64 s[16:17], s[8:9], s[16:17]
	s_and_b64 vcc, exec, s[16:17]
	s_cbranch_vccnz .LBB0_796
	v_or_b32_e32 v0, s25, v71
	v_mad_u64_u32 v[134:135], s[16:17], v0, s19, v[70:71]
	ds_read_b128 v[34:37], v134
	ds_read_b128 v[130:133], v134 offset:32
	v_or_b32_e32 v0, s25, v78
	v_cmp_lt_i32_e32 vcc, s3, v0
	s_or_b64 s[22:23], s[10:11], vcc
	v_mov_b32_e32 v129, 0xff800000
	s_waitcnt vmcnt(3) lgkmcnt(1)
	v_mfma_f32_32x32x16_bf16 v[34:49], v[34:37], v[62:65], 0
	s_waitcnt vmcnt(2) lgkmcnt(0)
	v_mfma_f32_32x32x16_bf16 v[34:49], v[130:133], v[58:61], v[34:49]
	ds_read_b128 v[130:133], v134 offset:64
	s_waitcnt vmcnt(1) lgkmcnt(0)
	v_mfma_f32_32x32x16_bf16 v[34:49], v[130:133], v[54:57], v[34:49]
	ds_read_b128 v[130:133], v134 offset:96
	s_waitcnt vmcnt(0) lgkmcnt(0)
	v_mfma_f32_32x32x16_bf16 v[34:49], v[130:133], v[50:53], v[34:49]
	v_mov_b32_e32 v130, 0xff800000
	s_cmp_eq_u64 s[10:11], -1
	s_cbranch_scc1 .Lswa_fast0
	s_and_saveexec_b64 s[16:17], s[22:23]
	s_cbranch_execz .LBB0_761
	ds_read_b32 v130, v80 offset:384
	s_waitcnt lgkmcnt(0)
	s_nop 6
	v_add_f32_e32 v130, v34, v130

; __device__ __forceinline__ float xhalf_max(float x) { float a, b; xhalf_swap(x, a, b); float m; asm("v_max3_f32 %0, %1, %2, %3" : "=v"(m) : "v"(x), "v"(a), "v"(b)); return m; }
; __device__ __forceinline__ void swa_unit(LAS unsigned char* lds, const bf16_t* Z1, const bf16_t* VTA, const float* bias2, const float* sinks, bf16_t* OA, int b, int kvh, int qblk, int wv) {
;     ...
;             const float mx = xhalf_max(max16(sc));
;             float alpha = 1.0f;
;             if (__any(mx > m + RESCALE_THR)) {
;                 const float mn = fmaxf(m, mx); alpha = __builtin_amdgcn_exp2f(m - mn); m = mn;
; #pragma unroll
;                 for (int i = 0; i < 16; ++i) { o0[i] *= alpha; o1[i] *= alpha; }
;             }
.Lswa_end0:
	v_max3_f32 v0, v130, v129, v35
	v_max3_f32 v48, v34, v37, v36
	v_max3_f32 v49, v39, v38, v41
	v_max3_f32 v131, v40, v43, v42
	v_max3_f32 v132, v45, v44, v47
	s_nop 0
	v_max3_f32 v0, v0, v48, v49
	v_max3_f32 v48, v131, v132, v46
	s_nop 0
	v_max3_f32 v0, v0, v48, v46
	s_nop 0
	v_mov_b32_e32 v48, v0
	v_mov_b32_e32 v49, v0
	s_nop 1
	v_permlane32_swap_b32 v48, v49
	s_nop 1
	s_nop 0
	v_max3_f32 v0, v0, v48, v49
	v_add_f32_e32 v48, 0x40c00000, v128
	v_cmp_gt_f32_e32 vcc, v0, v48
	s_cbranch_vccz .LBB0_794
	v_max_f32_e32 v0, v0, v0
	v_max_f32_e32 v48, v128, v128
	v_max_f32_e32 v48, v48, v0
	v_sub_f32_e32 v0, v128, v48
	v_exp_f32_e32 v0, v0
	v_mov_b32_e32 v128, v48
	v_pk_mul_f32 v[32:33], v[32:33], v[0:1] op_sel_hi:[1,0]
	v_pk_mul_f32 v[30:31], v[30:31], v[0:1] op_sel_hi:[1,0]
	v_pk_mul_f32 v[28:29], v[28:29], v[0:1] op_sel_hi:[1,0]
	v_pk_mul_f32 v[26:27], v[26:27], v[0:1] op_sel_hi:[1,0]
	v_pk_mul_f32 v[24:25], v[24:25], v[0:1] op_sel_hi:[1,0]
	v_pk_mul_f32 v[22:23], v[22:23], v[0:1] op_sel_hi:[1,0]
	v_pk_mul_f32 v[20:21], v[20:21], v[0:1] op_sel_hi:[1,0]
	v_pk_mul_f32 v[18:19], v[18:19], v[0:1] op_sel_hi:[1,0]
	v_pk_mul_f32 v[16:17], v[16:17], v[0:1] op_sel_hi:[1,0]
	v_pk_mul_f32 v[14:15], v[14:15], v[0:1] op_sel_hi:[1,0]
	v_pk_mul_f32 v[12:13], v[12:13], v[0:1] op_sel_hi:[1,0]
	v_pk_mul_f32 v[10:11], v[10:11], v[0:1] op_sel_hi:[1,0]
	v_pk_mul_f32 v[8:9], v[8:9], v[0:1] op_sel_hi:[1,0]
	v_pk_mul_f32 v[6:7], v[6:7], v[0:1] op_sel_hi:[1,0]
	v_pk_mul_f32 v[4:5], v[4:5], v[0:1] op_sel_hi:[1,0]
	v_pk_mul_f32 v[2:3], v[2:3], v[0:1] op_sel_hi:[1,0]
	s_branch .LBB0_795

; #define LAS __attribute__((address_space(3)))
; #define MFMA32(a, b, c) __builtin_amdgcn_mfma_f32_32x32x16_bf16((a), (b), (c), 0, 0, 0)
; __device__ __forceinline__ int crow(int i, int hh) { return (i & 3) + 8 * (i >> 2) + 4 * hh; }
; __device__ __forceinline__ void swa_unit(LAS unsigned char* lds, const bf16_t* Z1, const bf16_t* VTA, const float* bias2, const float* sinks, bf16_t* OA, int b, int kvh, int qblk, int wv) {
;     ...
;         for (int kt = 0; kt < 5; ++kt) {
;             const int kb = q0w + 32 * kt;
;             if (Q0 == 0 && kb + 31 < 128) continue;
;             f32x16 sc;
; #pragma unroll
;             for (int i = 0; i < 16; ++i) sc[i] = 0.f;
; #pragma unroll
;             for (int s = 0; s < 4; ++s) { const bf16x8 a = *(const LAS bf16x8*)(lds + (kb + r) * SK_ROW + s * 32 + hh * 16); sc = MFMA32(a, qf[s], sc); }
; #pragma unroll
;             for (int i = 0; i < 16; ++i) { const int c = crow(i, hh), dist = 128 - 32 * kt + r - c;
;                 const bool ok = (dist >= 0) && (dist < 128) && (Q0 > 0 || kb + c >= 128);
;                 sc[i] = ok ? sc[i] + bl[dist & 127] : -INFINITY; }
.LBB0_796:
	s_add_i32 s25, s30, 64
	s_or_b32 s16, s25, 31
	s_cmpk_lt_i32 s16, 0x80
	s_cselect_b64 s[16:17], -1, 0
	s_and_b64 s[16:17], s[8:9], s[16:17]
	s_and_b64 vcc, exec, s[16:17]
	s_cbranch_vccnz .LBB0_833
	v_or_b32_e32 v0, s25, v71
	v_mad_u64_u32 v[134:135], s[16:17], v0, s19, v[70:71]
	ds_read_b128 v[34:37], v134
	ds_read_b128 v[130:133], v134 offset:32
	v_or_b32_e32 v0, s25, v78
	v_cmp_lt_i32_e32 vcc, s3, v0
	s_or_b64 s[22:23], s[10:11], vcc
	v_mov_b32_e32 v129, 0xff800000
	s_waitcnt vmcnt(3) lgkmcnt(1)
	v_mfma_f32_32x32x16_bf16 v[34:49], v[34:37], v[62:65], 0
	s_waitcnt vmcnt(2) lgkmcnt(0)
	v_mfma_f32_32x32x16_bf16 v[34:49], v[130:133], v[58:61], v[34:49]
	ds_read_b128 v[130:133], v134 offset:64
	s_waitcnt vmcnt(1) lgkmcnt(0)
	v_mfma_f32_32x32x16_bf16 v[34:49], v[130:133], v[54:57], v[34:49]
	ds_read_b128 v[130:133], v134 offset:96
	s_waitcnt vmcnt(0) lgkmcnt(0)
	v_mfma_f32_32x32x16_bf16 v[34:49], v[130:133], v[50:53], v[34:49]
	v_mov_b32_e32 v130, 0xff800000
	s_cmp_eq_u64 s[10:11], -1
	s_cbranch_scc1 .Lswa_fast1
	s_and_saveexec_b64 s[16:17], s[22:23]
	s_cbranch_execz .LBB0_799
	ds_read_b32 v130, v80 offset:256
	s_waitcnt lgkmcnt(0)
	s_nop 6
	v_add_f32_e32 v130, v34, v130

; #define LAS __attribute__((address_space(3)))
; #define MFMA32(a, b, c) __builtin_amdgcn_mfma_f32_32x32x16_bf16((a), (b), (c), 0, 0, 0)
; __device__ __forceinline__ int crow(int i, int hh) { return (i & 3) + 8 * (i >> 2) + 4 * hh; }
; __device__ __forceinline__ void swa_unit(LAS unsigned char* lds, const bf16_t* Z1, const bf16_t* VTA, const float* bias2, const float* sinks, bf16_t* OA, int b, int kvh, int qblk, int wv) {
;     ...
;         for (int kt = 0; kt < 5; ++kt) {
;             const int kb = q0w + 32 * kt;
;             if (Q0 == 0 && kb + 31 < 128) continue;
;             f32x16 sc;
; #pragma unroll
;             for (int i = 0; i < 16; ++i) sc[i] = 0.f;
; #pragma unroll
;             for (int s = 0; s < 4; ++s) { const bf16x8 a = *(const LAS bf16x8*)(lds + (kb + r) * SK_ROW + s * 32 + hh * 16); sc = MFMA32(a, qf[s], sc); }
; #pragma unroll
;             for (int i = 0; i < 16; ++i) { const int c = crow(i, hh), dist = 128 - 32 * kt + r - c;
;                 const bool ok = (dist >= 0) && (dist < 128) && (Q0 > 0 || kb + c >= 128);
;                 sc[i] = ok ? sc[i] + bl[dist & 127] : -INFINITY; }
.LBB0_833:
	s_add_i32 s25, s30, 0x60
	s_or_b32 s16, s25, 31
	s_cmpk_lt_i32 s16, 0x80
	s_cselect_b64 s[16:17], -1, 0
	s_and_b64 s[16:17], s[8:9], s[16:17]
	s_and_b64 vcc, exec, s[16:17]
	s_cbranch_vccnz .LBB0_870
	v_or_b32_e32 v0, s25, v71
	v_mad_u64_u32 v[134:135], s[16:17], v0, s19, v[70:71]
	ds_read_b128 v[34:37], v134
	ds_read_b128 v[130:133], v134 offset:32
	v_or_b32_e32 v0, s25, v78
	v_cmp_lt_i32_e32 vcc, s3, v0
	s_or_b64 s[22:23], s[10:11], vcc
	v_mov_b32_e32 v129, 0xff800000
	s_waitcnt vmcnt(3) lgkmcnt(1)
	v_mfma_f32_32x32x16_bf16 v[34:49], v[34:37], v[62:65], 0
	s_waitcnt vmcnt(2) lgkmcnt(0)
	v_mfma_f32_32x32x16_bf16 v[34:49], v[130:133], v[58:61], v[34:49]
	ds_read_b128 v[130:133], v134 offset:64
	s_waitcnt vmcnt(1) lgkmcnt(0)
	v_mfma_f32_32x32x16_bf16 v[34:49], v[130:133], v[54:57], v[34:49]
	ds_read_b128 v[130:133], v134 offset:96
	s_waitcnt vmcnt(0) lgkmcnt(0)
	v_mfma_f32_32x32x16_bf16 v[34:49], v[130:133], v[50:53], v[34:49]
	v_mov_b32_e32 v130, 0xff800000
	s_cmp_eq_u64 s[10:11], -1
	s_cbranch_scc1 .Lswa_fast2
	s_and_saveexec_b64 s[16:17], s[22:23]
	s_cbranch_execz .LBB0_836
	ds_read_b32 v130, v80 offset:128
	s_waitcnt lgkmcnt(0)
	s_nop 6
	v_add_f32_e32 v130, v34, v130

; __device__ __forceinline__ int crow(int i, int hh) { return (i & 3) + 8 * (i >> 2) + 4 * hh; }
; __device__ __forceinline__ void swa_unit(LAS unsigned char* lds, const bf16_t* Z1, const bf16_t* VTA, const float* bias2, const float* sinks, bf16_t* OA, int b, int kvh, int qblk, int wv) {
;     ...
;             for (int i = 0; i < 16; ++i) { const int c = crow(i, hh), dist = 128 - 32 * kt + r - c;
;                 const bool ok = (dist >= 0) && (dist < 128) && (Q0 > 0 || kb + c >= 128);
;                 sc[i] = ok ? sc[i] + bl[dist & 127] : -INFINITY; }
.Lswa_fast0:
	ds_read_b32 v144, v80 offset:384
	ds_read_b32 v145, v80 offset:380
	ds_read_b32 v146, v80 offset:376
	ds_read_b32 v147, v80 offset:372
	ds_read_b32 v148, v80 offset:352
	ds_read_b32 v149, v80 offset:348
	ds_read_b32 v150, v80 offset:344
	ds_read_b32 v151, v80 offset:340
	ds_read_b32 v152, v80 offset:320
	ds_read_b32 v153, v80 offset:316
	ds_read_b32 v154, v80 offset:312
	ds_read_b32 v155, v80 offset:308
	ds_read_b32 v156, v80 offset:288
	ds_read_b32 v157, v80 offset:284
	ds_read_b32 v158, v80 offset:280
	ds_read_b32 v159, v80 offset:276
	s_waitcnt lgkmcnt(0)
	v_add_f32_e32 v130, v34, v144
	v_add_f32_e32 v129, v35, v145
	v_add_f32_e32 v35, v36, v146
	v_add_f32_e32 v34, v37, v147
	v_add_f32_e32 v37, v38, v148
	v_add_f32_e32 v36, v39, v149
	v_add_f32_e32 v39, v40, v150
	v_add_f32_e32 v38, v41, v151
	v_add_f32_e32 v41, v42, v152
	v_add_f32_e32 v40, v43, v153
	v_add_f32_e32 v43, v44, v154
	v_add_f32_e32 v42, v45, v155
	v_add_f32_e32 v45, v46, v156
	v_add_f32_e32 v44, v47, v157
	v_add_f32_e32 v47, v48, v158
	v_add_f32_e32 v46, v49, v159
	s_branch .Lswa_end0
.Lswa_fast1:
	ds_read_b32 v144, v80 offset:256
	ds_read_b32 v145, v80 offset:252
	ds_read_b32 v146, v80 offset:248
	ds_read_b32 v147, v80 offset:244
	ds_read_b32 v148, v80 offset:224
	ds_read_b32 v149, v80 offset:220
	ds_read_b32 v150, v80 offset:216
	ds_read_b32 v151, v80 offset:212
	ds_read_b32 v152, v80 offset:192
	ds_read_b32 v153, v80 offset:188
	ds_read_b32 v154, v80 offset:184
	ds_read_b32 v155, v80 offset:180
	ds_read_b32 v156, v80 offset:160
	ds_read_b32 v157, v80 offset:156
	ds_read_b32 v158, v80 offset:152
	ds_read_b32 v159, v80 offset:148
	s_waitcnt lgkmcnt(0)
	v_add_f32_e32 v130, v34, v144
	v_add_f32_e32 v129, v35, v145
	v_add_f32_e32 v35, v36, v146
	v_add_f32_e32 v34, v37, v147
	v_add_f32_e32 v37, v38, v148
	v_add_f32_e32 v36, v39, v149
	v_add_f32_e32 v39, v40, v150
	v_add_f32_e32 v38, v41, v151
	v_add_f32_e32 v41, v42, v152
	v_add_f32_e32 v40, v43, v153
	v_add_f32_e32 v43, v44, v154
	v_add_f32_e32 v42, v45, v155
	v_add_f32_e32 v45, v46, v156
	v_add_f32_e32 v44, v47, v157
	v_add_f32_e32 v47, v48, v158
	v_add_f32_e32 v46, v49, v159
	s_branch .Lswa_end1
.Lswa_fast2:
	ds_read_b32 v144, v80 offset:128
	ds_read_b32 v145, v80 offset:124
	ds_read_b32 v146, v80 offset:120
	ds_read_b32 v147, v80 offset:116
	ds_read_b32 v148, v80 offset:96
	ds_read_b32 v149, v80 offset:92
	ds_read_b32 v150, v80 offset:88
	ds_read_b32 v151, v80 offset:84
	ds_read_b32 v152, v80 offset:64
	ds_read_b32 v153, v80 offset:60
	ds_read_b32 v154, v80 offset:56
	ds_read_b32 v155, v80 offset:52
	ds_read_b32 v156, v80 offset:32
	ds_read_b32 v157, v80 offset:28
	ds_read_b32 v158, v80 offset:24
	ds_read_b32 v159, v80 offset:20
	s_waitcnt lgkmcnt(0)
	v_add_f32_e32 v130, v34, v144
	v_add_f32_e32 v129, v35, v145
	v_add_f32_e32 v35, v36, v146
	v_add_f32_e32 v34, v37, v147
	v_add_f32_e32 v37, v38, v148
	v_add_f32_e32 v36, v39, v149
	v_add_f32_e32 v39, v40, v150
	v_add_f32_e32 v38, v41, v151
	v_add_f32_e32 v41, v42, v152
	v_add_f32_e32 v40, v43, v153
	v_add_f32_e32 v43, v44, v154
	v_add_f32_e32 v42, v45, v155
	v_add_f32_e32 v45, v46, v156
	v_add_f32_e32 v44, v47, v157
	v_add_f32_e32 v47, v48, v158
	v_add_f32_e32 v46, v49, v159
	s_branch .Lswa_end2
